# code placement: the five GEMM K-loop heads aligned to 64 bytes (.p2align 6)
# baseline (speedup 1.0000x reference)
.LBB0_468:
	s_ashr_i32 s23, s22, 31
	s_lshl_b64 s[56:57], s[22:23], 19
	s_add_u32 s80, s45, s56
	s_addc_u32 s81, s84, s57
	s_and_b64 s[56:57], s[4:5], exec
	s_cselect_b32 s1, s81, s35
	s_cselect_b32 s13, s80, s34
	s_ashr_i32 s25, s24, 31
	s_lshl_b64 s[56:57], s[24:25], 19
	s_add_u32 s82, s85, s56
	s_addc_u32 s83, s86, s57
	s_and_b64 s[56:57], s[4:5], exec
	s_cselect_b32 s23, s83, s7
	s_cselect_b32 s25, s82, s6
	s_add_u32 s66, s6, 0x100
	s_addc_u32 s67, s7, 0
	s_add_u32 s6, s34, 0x40080
	v_mov_b32_e32 v0, 0
	s_addc_u32 s7, s35, 0
	s_mov_b32 s76, -2
	v_mov_b32_e32 v1, v0
	v_mov_b32_e32 v2, v0
	v_mov_b32_e32 v3, v0
	v_mov_b32_e32 v4, v0
	v_mov_b32_e32 v5, v0
	v_mov_b32_e32 v6, v0
	v_mov_b32_e32 v7, v0
	v_mov_b32_e32 v16, v0
	v_mov_b32_e32 v17, v0
	v_mov_b32_e32 v18, v0
	v_mov_b32_e32 v19, v0
	v_mov_b32_e32 v20, v0
	v_mov_b32_e32 v21, v0
	v_mov_b32_e32 v22, v0
	v_mov_b32_e32 v23, v0
	v_mov_b32_e32 v48, v0
	v_mov_b32_e32 v49, v0
	v_mov_b32_e32 v50, v0
	v_mov_b32_e32 v51, v0
	v_mov_b32_e32 v52, v0
	v_mov_b32_e32 v53, v0
	v_mov_b32_e32 v54, v0
	v_mov_b32_e32 v55, v0
	v_mov_b32_e32 v66, v0
	v_mov_b32_e32 v67, v0
	v_mov_b32_e32 v68, v0
	v_mov_b32_e32 v69, v0
	v_mov_b32_e32 v70, v0
	v_mov_b32_e32 v71, v0
	v_mov_b32_e32 v72, v0
	v_mov_b32_e32 v73, v0
	v_mov_b32_e32 v8, v0
	v_mov_b32_e32 v9, v0
	v_mov_b32_e32 v10, v0
	v_mov_b32_e32 v11, v0
	v_mov_b32_e32 v12, v0
	v_mov_b32_e32 v13, v0
	v_mov_b32_e32 v14, v0
	v_mov_b32_e32 v15, v0
	v_mov_b32_e32 v32, v0
	v_mov_b32_e32 v33, v0
	v_mov_b32_e32 v34, v0
	v_mov_b32_e32 v35, v0
	v_mov_b32_e32 v44, v0
	v_mov_b32_e32 v45, v0
	v_mov_b32_e32 v46, v0
	v_mov_b32_e32 v47, v0
	v_mov_b32_e32 v56, v0
	v_mov_b32_e32 v57, v0
	v_mov_b32_e32 v58, v0
	v_mov_b32_e32 v59, v0
	v_mov_b32_e32 v60, v0
	v_mov_b32_e32 v61, v0
	v_mov_b32_e32 v62, v0
	v_mov_b32_e32 v63, v0
	v_mov_b32_e32 v74, v0
	v_mov_b32_e32 v75, v0
	v_mov_b32_e32 v76, v0
	v_mov_b32_e32 v77, v0
	v_mov_b32_e32 v78, v0
	v_mov_b32_e32 v79, v0
	v_mov_b32_e32 v80, v0
	v_mov_b32_e32 v81, v0
	v_mov_b32_e32 v82, v0
	v_mov_b32_e32 v83, v0
	v_mov_b32_e32 v84, v0
	v_mov_b32_e32 v85, v0
	v_mov_b32_e32 v86, v0
	v_mov_b32_e32 v87, v0
	v_mov_b32_e32 v88, v0
	v_mov_b32_e32 v89, v0
	v_mov_b32_e32 v98, v0
	v_mov_b32_e32 v99, v0
	v_mov_b32_e32 v100, v0
	v_mov_b32_e32 v101, v0
	v_mov_b32_e32 v102, v0
	v_mov_b32_e32 v103, v0
	v_mov_b32_e32 v104, v0
	v_mov_b32_e32 v105, v0
	v_mov_b32_e32 v114, v0
	v_mov_b32_e32 v115, v0
	v_mov_b32_e32 v116, v0
	v_mov_b32_e32 v117, v0
	v_mov_b32_e32 v118, v0
	v_mov_b32_e32 v119, v0
	v_mov_b32_e32 v120, v0
	v_mov_b32_e32 v121, v0
	v_mov_b32_e32 v130, v0
	v_mov_b32_e32 v131, v0
	v_mov_b32_e32 v132, v0
	v_mov_b32_e32 v133, v0
	v_mov_b32_e32 v134, v0
	v_mov_b32_e32 v135, v0
	v_mov_b32_e32 v136, v0
	v_mov_b32_e32 v137, v0
	v_mov_b32_e32 v90, v0
	v_mov_b32_e32 v91, v0
	v_mov_b32_e32 v92, v0
	v_mov_b32_e32 v93, v0
	v_mov_b32_e32 v94, v0
	v_mov_b32_e32 v95, v0
	v_mov_b32_e32 v96, v0
	v_mov_b32_e32 v97, v0
	v_mov_b32_e32 v106, v0
	v_mov_b32_e32 v107, v0
	v_mov_b32_e32 v108, v0
	v_mov_b32_e32 v109, v0
	v_mov_b32_e32 v110, v0
	v_mov_b32_e32 v111, v0
	v_mov_b32_e32 v112, v0
	v_mov_b32_e32 v113, v0
	v_mov_b32_e32 v122, v0
	v_mov_b32_e32 v123, v0
	v_mov_b32_e32 v124, v0
	v_mov_b32_e32 v125, v0
	v_mov_b32_e32 v126, v0
	v_mov_b32_e32 v127, v0
	v_mov_b32_e32 v128, v0
	v_mov_b32_e32 v129, v0
	v_mov_b32_e32 v138, v0
	v_mov_b32_e32 v139, v0
	v_mov_b32_e32 v140, v0
	v_mov_b32_e32 v141, v0
	v_mov_b32_e32 v142, v0
	v_mov_b32_e32 v143, v0
	v_mov_b32_e32 v144, v0
	v_mov_b32_e32 v145, v0
	.p2align 6

.LBB0_1825:
	v_bfe_u32 v147, v8, 4, 2
	s_lshl_b32 s24, s24, 5
	v_and_b32_e32 v146, 15, v8
	s_lshl_b32 s17, s22, 6
	v_lshlrev_b32_e32 v11, 4, v147
	v_lshlrev_b32_e32 v8, 2, v8
	s_lshl_b32 s25, s22, 13
	s_and_b32 s22, s24, 0x60
	v_lshl_or_b32 v11, v146, 6, v11
	v_and_b32_e32 v8, 32, v8
	s_lshl_b32 s24, s22, 7
	v_bitop3_b32 v58, v11, s24, v8 bitop3:0xde
	s_add_u32 s24, s14, 0xc00080
	v_mov_b32_e32 v45, v65
	v_bitop3_b32 v8, v11, s25, v8 bitop3:0xde
	s_addc_u32 s25, s15, 0
	v_mov_b32_e32 v49, v65
	s_add_i32 m0, s19, 0x18000
	v_lshl_add_u64 v[12:13], s[24:25], 0, v[44:45]
	s_waitcnt vmcnt(2)
	s_barrier
	global_load_lds_dwordx4 v[12:13], off
	v_lshl_add_u64 v[12:13], s[24:25], 0, v[48:49]
	s_add_i32 m0, s19, 0x1a000
	s_add_i32 s24, s19, 0x8000
	s_add_i32 s25, s19, 0xa000
	global_load_lds_dwordx4 v[12:13], off
	v_lshl_add_u64 v[2:3], v[2:3], 0, s[30:31]
	s_mov_b32 m0, s24
	s_add_u32 s14, s14, 0xc40080
	global_load_lds_dwordx4 v[2:3], off
	v_lshl_add_u64 v[0:1], v[0:1], 0, s[30:31]
	s_mov_b32 m0, s25
	s_addc_u32 s15, s15, 0
	global_load_lds_dwordx4 v[0:1], off
	s_add_i32 m0, s19, 0x1c000
	v_lshl_add_u64 v[0:1], s[14:15], 0, v[44:45]
	global_load_lds_dwordx4 v[0:1], off
	v_lshl_add_u64 v[0:1], s[14:15], 0, v[48:49]
	s_add_i32 m0, s19, 0x1e000
	s_add_u32 s13, s6, s13
	global_load_lds_dwordx4 v[0:1], off
	s_addc_u32 s12, s7, s12
	s_add_u32 s33, s13, 0xc00100
	s_addc_u32 s34, s12, 0
	v_lshlrev_b32_e32 v0, 14, v7
	v_and_b32_e32 v0, 0xffff8000, v0
	s_add_u32 s35, s6, s10
	v_lshl_add_u32 v0, v9, 11, v0
	v_and_b32_e32 v1, 1, v7
	s_addc_u32 s44, s7, s11
	v_lshl_or_b32 v0, v1, 6, v0
	s_add_u32 s10, s35, 0x9640080
	v_lshl_add_u32 v0, v10, 1, v0
	v_mov_b32_e32 v1, v65
	s_addc_u32 s11, s44, 0
	v_lshl_add_u64 v[50:51], s[10:11], 0, v[0:1]
	v_lshlrev_b32_e32 v0, 14, v4
	v_and_b32_e32 v0, 0xffff8000, v0
	v_lshl_add_u32 v0, v5, 11, v0
	v_and_b32_e32 v1, 1, v4
	v_lshl_or_b32 v0, v1, 6, v0
	s_waitcnt vmcnt(6)
	v_lshl_add_u32 v0, v6, 1, v0
	v_mov_b32_e32 v1, v65
	v_lshl_add_u64 v[56:57], s[10:11], 0, v[0:1]
	v_mov_b32_e32 v0, 0
	s_mov_b32 s53, -2
	s_mov_b64 s[10:11], 0
	v_add_u32_e32 v59, 0, v8
	v_mov_b32_e32 v1, v0
	v_mov_b32_e32 v2, v0
	v_mov_b32_e32 v3, v0
	v_mov_b32_e32 v4, v0
	v_mov_b32_e32 v5, v0
	v_mov_b32_e32 v6, v0
	v_mov_b32_e32 v7, v0
	v_mov_b32_e32 v16, v0
	v_mov_b32_e32 v17, v0
	v_mov_b32_e32 v18, v0
	v_mov_b32_e32 v19, v0
	v_mov_b32_e32 v20, v0
	v_mov_b32_e32 v21, v0
	v_mov_b32_e32 v22, v0
	v_mov_b32_e32 v23, v0
	v_mov_b32_e32 v32, v0
	v_mov_b32_e32 v33, v0
	v_mov_b32_e32 v34, v0
	v_mov_b32_e32 v35, v0
	v_mov_b32_e32 v36, v0
	v_mov_b32_e32 v37, v0
	v_mov_b32_e32 v38, v0
	v_mov_b32_e32 v39, v0
	v_mov_b32_e32 v66, v0
	v_mov_b32_e32 v67, v0
	v_mov_b32_e32 v68, v0
	v_mov_b32_e32 v69, v0
	v_mov_b32_e32 v70, v0
	v_mov_b32_e32 v71, v0
	v_mov_b32_e32 v72, v0
	v_mov_b32_e32 v73, v0
	v_mov_b32_e32 v8, v0
	v_mov_b32_e32 v9, v0
	v_mov_b32_e32 v10, v0
	v_mov_b32_e32 v11, v0
	v_mov_b32_e32 v12, v0
	v_mov_b32_e32 v13, v0
	v_mov_b32_e32 v14, v0
	v_mov_b32_e32 v15, v0
	v_mov_b32_e32 v24, v0
	v_mov_b32_e32 v25, v0
	v_mov_b32_e32 v26, v0
	v_mov_b32_e32 v27, v0
	v_mov_b32_e32 v28, v0
	v_mov_b32_e32 v29, v0
	v_mov_b32_e32 v30, v0
	v_mov_b32_e32 v31, v0
	v_mov_b32_e32 v40, v0
	v_mov_b32_e32 v41, v0
	v_mov_b32_e32 v42, v0
	v_mov_b32_e32 v43, v0
	v_mov_b32_e32 v52, v0
	v_mov_b32_e32 v53, v0
	v_mov_b32_e32 v54, v0
	v_mov_b32_e32 v55, v0
	v_mov_b32_e32 v74, v0
	v_mov_b32_e32 v75, v0
	v_mov_b32_e32 v76, v0
	v_mov_b32_e32 v77, v0
	v_mov_b32_e32 v78, v0
	v_mov_b32_e32 v79, v0
	v_mov_b32_e32 v80, v0
	v_mov_b32_e32 v81, v0
	v_mov_b32_e32 v82, v0
	v_mov_b32_e32 v83, v0
	v_mov_b32_e32 v84, v0
	v_mov_b32_e32 v85, v0
	v_mov_b32_e32 v86, v0
	v_mov_b32_e32 v87, v0
	v_mov_b32_e32 v88, v0
	v_mov_b32_e32 v89, v0
	v_mov_b32_e32 v98, v0
	v_mov_b32_e32 v99, v0
	v_mov_b32_e32 v100, v0
	v_mov_b32_e32 v101, v0
	v_mov_b32_e32 v102, v0
	v_mov_b32_e32 v103, v0
	v_mov_b32_e32 v104, v0
	v_mov_b32_e32 v105, v0
	v_mov_b32_e32 v114, v0
	v_mov_b32_e32 v115, v0
	v_mov_b32_e32 v116, v0
	v_mov_b32_e32 v117, v0
	v_mov_b32_e32 v118, v0
	v_mov_b32_e32 v119, v0
	v_mov_b32_e32 v120, v0
	v_mov_b32_e32 v121, v0
	v_mov_b32_e32 v130, v0
	v_mov_b32_e32 v131, v0
	v_mov_b32_e32 v132, v0
	v_mov_b32_e32 v133, v0
	v_mov_b32_e32 v134, v0
	v_mov_b32_e32 v135, v0
	v_mov_b32_e32 v136, v0
	v_mov_b32_e32 v137, v0
	v_mov_b32_e32 v90, v0
	v_mov_b32_e32 v91, v0
	v_mov_b32_e32 v92, v0
	v_mov_b32_e32 v93, v0
	v_mov_b32_e32 v94, v0
	v_mov_b32_e32 v95, v0
	v_mov_b32_e32 v96, v0
	v_mov_b32_e32 v97, v0
	v_mov_b32_e32 v106, v0
	v_mov_b32_e32 v107, v0
	v_mov_b32_e32 v108, v0
	v_mov_b32_e32 v109, v0
	v_mov_b32_e32 v110, v0
	v_mov_b32_e32 v111, v0
	v_mov_b32_e32 v112, v0
	v_mov_b32_e32 v113, v0
	v_mov_b32_e32 v122, v0
	v_mov_b32_e32 v123, v0
	v_mov_b32_e32 v124, v0
	v_mov_b32_e32 v125, v0
	v_mov_b32_e32 v126, v0
	v_mov_b32_e32 v127, v0
	v_mov_b32_e32 v128, v0
	v_mov_b32_e32 v129, v0
	v_mov_b32_e32 v138, v0
	v_mov_b32_e32 v139, v0
	v_mov_b32_e32 v140, v0
	v_mov_b32_e32 v141, v0
	v_mov_b32_e32 v142, v0
	v_mov_b32_e32 v143, v0
	v_mov_b32_e32 v144, v0
	v_mov_b32_e32 v145, v0
	s_barrier
	.p2align 6

.LBB0_1883:
	s_ashr_i32 s25, s24, 31
	s_lshl_b64 s[66:67], s[24:25], 19
	s_add_u32 s76, s4, s66
	s_addc_u32 s77, s5, s67
	s_and_b64 s[66:67], s[6:7], exec
	s_cselect_b32 s9, s77, s57
	s_cselect_b32 s25, s76, s56
	s_ashr_i32 s23, s22, 31
	s_lshl_b64 s[66:67], s[22:23], 19
	s_add_u32 s80, s33, s66
	s_addc_u32 s81, s44, s67
	s_and_b64 s[66:67], s[6:7], exec
	s_cselect_b32 s23, s81, s35
	s_cselect_b32 s66, s80, s34
	s_add_u32 s67, s34, 0x100
	s_addc_u32 s96, s35, 0
	s_add_u32 s56, s56, 0x40080
	v_mov_b32_e32 v0, 0
	s_addc_u32 s57, s57, 0
	s_mov_b32 vcc_lo, -2
	v_mov_b32_e32 v1, v0
	v_mov_b32_e32 v2, v0
	v_mov_b32_e32 v3, v0
	v_mov_b32_e32 v4, v0
	v_mov_b32_e32 v5, v0
	v_mov_b32_e32 v6, v0
	v_mov_b32_e32 v7, v0
	v_mov_b32_e32 v16, v0
	v_mov_b32_e32 v17, v0
	v_mov_b32_e32 v18, v0
	v_mov_b32_e32 v19, v0
	v_mov_b32_e32 v20, v0
	v_mov_b32_e32 v21, v0
	v_mov_b32_e32 v22, v0
	v_mov_b32_e32 v23, v0
	v_mov_b32_e32 v32, v0
	v_mov_b32_e32 v33, v0
	v_mov_b32_e32 v34, v0
	v_mov_b32_e32 v35, v0
	v_mov_b32_e32 v36, v0
	v_mov_b32_e32 v37, v0
	v_mov_b32_e32 v38, v0
	v_mov_b32_e32 v39, v0
	v_mov_b32_e32 v48, v0
	v_mov_b32_e32 v49, v0
	v_mov_b32_e32 v50, v0
	v_mov_b32_e32 v51, v0
	v_mov_b32_e32 v52, v0
	v_mov_b32_e32 v53, v0
	v_mov_b32_e32 v54, v0
	v_mov_b32_e32 v55, v0
	v_mov_b32_e32 v8, v0
	v_mov_b32_e32 v9, v0
	v_mov_b32_e32 v10, v0
	v_mov_b32_e32 v11, v0
	v_mov_b32_e32 v12, v0
	v_mov_b32_e32 v13, v0
	v_mov_b32_e32 v14, v0
	v_mov_b32_e32 v15, v0
	v_mov_b32_e32 v24, v0
	v_mov_b32_e32 v25, v0
	v_mov_b32_e32 v26, v0
	v_mov_b32_e32 v27, v0
	v_mov_b32_e32 v28, v0
	v_mov_b32_e32 v29, v0
	v_mov_b32_e32 v30, v0
	v_mov_b32_e32 v31, v0
	v_mov_b32_e32 v40, v0
	v_mov_b32_e32 v41, v0
	v_mov_b32_e32 v42, v0
	v_mov_b32_e32 v43, v0
	v_mov_b32_e32 v44, v0
	v_mov_b32_e32 v45, v0
	v_mov_b32_e32 v46, v0
	v_mov_b32_e32 v47, v0
	v_mov_b32_e32 v90, v0
	v_mov_b32_e32 v91, v0
	v_mov_b32_e32 v92, v0
	v_mov_b32_e32 v93, v0
	v_mov_b32_e32 v94, v0
	v_mov_b32_e32 v95, v0
	v_mov_b32_e32 v96, v0
	v_mov_b32_e32 v97, v0
	v_mov_b32_e32 v98, v0
	v_mov_b32_e32 v99, v0
	v_mov_b32_e32 v100, v0
	v_mov_b32_e32 v101, v0
	v_mov_b32_e32 v102, v0
	v_mov_b32_e32 v103, v0
	v_mov_b32_e32 v104, v0
	v_mov_b32_e32 v105, v0
	v_mov_b32_e32 v114, v0
	v_mov_b32_e32 v115, v0
	v_mov_b32_e32 v116, v0
	v_mov_b32_e32 v117, v0
	v_mov_b32_e32 v118, v0
	v_mov_b32_e32 v119, v0
	v_mov_b32_e32 v120, v0
	v_mov_b32_e32 v121, v0
	v_mov_b32_e32 v130, v0
	v_mov_b32_e32 v131, v0
	v_mov_b32_e32 v132, v0
	v_mov_b32_e32 v133, v0
	v_mov_b32_e32 v134, v0
	v_mov_b32_e32 v135, v0
	v_mov_b32_e32 v136, v0
	v_mov_b32_e32 v137, v0
	v_mov_b32_e32 v146, v0
	v_mov_b32_e32 v147, v0
	v_mov_b32_e32 v148, v0
	v_mov_b32_e32 v149, v0
	v_mov_b32_e32 v150, v0
	v_mov_b32_e32 v151, v0
	v_mov_b32_e32 v152, v0
	v_mov_b32_e32 v153, v0
	v_mov_b32_e32 v106, v0
	v_mov_b32_e32 v107, v0
	v_mov_b32_e32 v108, v0
	v_mov_b32_e32 v109, v0
	v_mov_b32_e32 v110, v0
	v_mov_b32_e32 v111, v0
	v_mov_b32_e32 v112, v0
	v_mov_b32_e32 v113, v0
	v_mov_b32_e32 v122, v0
	v_mov_b32_e32 v123, v0
	v_mov_b32_e32 v124, v0
	v_mov_b32_e32 v125, v0
	v_mov_b32_e32 v126, v0
	v_mov_b32_e32 v127, v0
	v_mov_b32_e32 v128, v0
	v_mov_b32_e32 v129, v0
	v_mov_b32_e32 v138, v0
	v_mov_b32_e32 v139, v0
	v_mov_b32_e32 v140, v0
	v_mov_b32_e32 v141, v0
	v_mov_b32_e32 v142, v0
	v_mov_b32_e32 v143, v0
	v_mov_b32_e32 v144, v0
	v_mov_b32_e32 v145, v0
	v_mov_b32_e32 v154, v0
	v_mov_b32_e32 v155, v0
	v_mov_b32_e32 v156, v0
	v_mov_b32_e32 v157, v0
	v_mov_b32_e32 v158, v0
	v_mov_b32_e32 v159, v0
	v_mov_b32_e32 v160, v0
	v_mov_b32_e32 v161, v0
	.p2align 6

.LBB0_2124:
	s_ashr_i32 s83, s82, 31
	s_lshl_b64 s[0:1], s[82:83], 19
	s_add_u32 s84, s33, s0
	s_addc_u32 s85, s44, s1
	s_and_b64 s[0:1], s[6:7], exec
	s_cselect_b32 s13, s85, s57
	s_cselect_b32 s66, s84, s56
	s_ashr_i32 s81, s80, 31
	s_lshl_b64 s[0:1], s[80:81], 19
	s_add_u32 s86, s45, s0
	s_addc_u32 s87, s53, s1
	s_and_b64 s[0:1], s[6:7], exec
	s_cselect_b32 s67, s87, s35
	s_cselect_b32 s81, s86, s34
	s_add_u32 s83, s34, 0x100
	s_addc_u32 s96, s35, 0
	s_add_u32 s56, s56, 0x40080
	v_mov_b32_e32 v0, 0
	s_addc_u32 s57, s57, 0
	s_mov_b32 vcc_lo, -2
	v_mov_b32_e32 v1, v0
	v_mov_b32_e32 v2, v0
	v_mov_b32_e32 v3, v0
	v_mov_b32_e32 v4, v0
	v_mov_b32_e32 v5, v0
	v_mov_b32_e32 v6, v0
	v_mov_b32_e32 v7, v0
	v_mov_b32_e32 v16, v0
	v_mov_b32_e32 v17, v0
	v_mov_b32_e32 v18, v0
	v_mov_b32_e32 v19, v0
	v_mov_b32_e32 v20, v0
	v_mov_b32_e32 v21, v0
	v_mov_b32_e32 v22, v0
	v_mov_b32_e32 v23, v0
	v_mov_b32_e32 v48, v0
	v_mov_b32_e32 v49, v0
	v_mov_b32_e32 v50, v0
	v_mov_b32_e32 v51, v0
	v_mov_b32_e32 v52, v0
	v_mov_b32_e32 v53, v0
	v_mov_b32_e32 v54, v0
	v_mov_b32_e32 v55, v0
	v_mov_b32_e32 v66, v0
	v_mov_b32_e32 v67, v0
	v_mov_b32_e32 v68, v0
	v_mov_b32_e32 v69, v0
	v_mov_b32_e32 v70, v0
	v_mov_b32_e32 v71, v0
	v_mov_b32_e32 v72, v0
	v_mov_b32_e32 v73, v0
	v_mov_b32_e32 v8, v0
	v_mov_b32_e32 v9, v0
	v_mov_b32_e32 v10, v0
	v_mov_b32_e32 v11, v0
	v_mov_b32_e32 v12, v0
	v_mov_b32_e32 v13, v0
	v_mov_b32_e32 v14, v0
	v_mov_b32_e32 v15, v0
	v_mov_b32_e32 v24, v0
	v_mov_b32_e32 v25, v0
	v_mov_b32_e32 v26, v0
	v_mov_b32_e32 v27, v0
	v_mov_b32_e32 v28, v0
	v_mov_b32_e32 v29, v0
	v_mov_b32_e32 v30, v0
	v_mov_b32_e32 v31, v0
	v_mov_b32_e32 v56, v0
	v_mov_b32_e32 v57, v0
	v_mov_b32_e32 v58, v0
	v_mov_b32_e32 v59, v0
	v_mov_b32_e32 v60, v0
	v_mov_b32_e32 v61, v0
	v_mov_b32_e32 v62, v0
	v_mov_b32_e32 v63, v0
	v_mov_b32_e32 v74, v0
	v_mov_b32_e32 v75, v0
	v_mov_b32_e32 v76, v0
	v_mov_b32_e32 v77, v0
	v_mov_b32_e32 v78, v0
	v_mov_b32_e32 v79, v0
	v_mov_b32_e32 v80, v0
	v_mov_b32_e32 v81, v0
	v_mov_b32_e32 v82, v0
	v_mov_b32_e32 v83, v0
	v_mov_b32_e32 v84, v0
	v_mov_b32_e32 v85, v0
	v_mov_b32_e32 v86, v0
	v_mov_b32_e32 v87, v0
	v_mov_b32_e32 v88, v0
	v_mov_b32_e32 v89, v0
	v_mov_b32_e32 v98, v0
	v_mov_b32_e32 v99, v0
	v_mov_b32_e32 v100, v0
	v_mov_b32_e32 v101, v0
	v_mov_b32_e32 v102, v0
	v_mov_b32_e32 v103, v0
	v_mov_b32_e32 v104, v0
	v_mov_b32_e32 v105, v0
	v_mov_b32_e32 v114, v0
	v_mov_b32_e32 v115, v0
	v_mov_b32_e32 v116, v0
	v_mov_b32_e32 v117, v0
	v_mov_b32_e32 v118, v0
	v_mov_b32_e32 v119, v0
	v_mov_b32_e32 v120, v0
	v_mov_b32_e32 v121, v0
	v_mov_b32_e32 v130, v0
	v_mov_b32_e32 v131, v0
	v_mov_b32_e32 v132, v0
	v_mov_b32_e32 v133, v0
	v_mov_b32_e32 v134, v0
	v_mov_b32_e32 v135, v0
	v_mov_b32_e32 v136, v0
	v_mov_b32_e32 v137, v0
	v_mov_b32_e32 v90, v0
	v_mov_b32_e32 v91, v0
	v_mov_b32_e32 v92, v0
	v_mov_b32_e32 v93, v0
	v_mov_b32_e32 v94, v0
	v_mov_b32_e32 v95, v0
	v_mov_b32_e32 v96, v0
	v_mov_b32_e32 v97, v0
	v_mov_b32_e32 v106, v0
	v_mov_b32_e32 v107, v0
	v_mov_b32_e32 v108, v0
	v_mov_b32_e32 v109, v0
	v_mov_b32_e32 v110, v0
	v_mov_b32_e32 v111, v0
	v_mov_b32_e32 v112, v0
	v_mov_b32_e32 v113, v0
	v_mov_b32_e32 v122, v0
	v_mov_b32_e32 v123, v0
	v_mov_b32_e32 v124, v0
	v_mov_b32_e32 v125, v0
	v_mov_b32_e32 v126, v0
	v_mov_b32_e32 v127, v0
	v_mov_b32_e32 v128, v0
	v_mov_b32_e32 v129, v0
	v_mov_b32_e32 v138, v0
	v_mov_b32_e32 v139, v0
	v_mov_b32_e32 v140, v0
	v_mov_b32_e32 v141, v0
	v_mov_b32_e32 v142, v0
	v_mov_b32_e32 v143, v0
	v_mov_b32_e32 v144, v0
	v_mov_b32_e32 v145, v0
	.p2align 6

.LBB0_2177:
	s_ashr_i32 s57, s56, 31
	s_lshl_b64 s[8:9], s[56:57], 21
	s_add_u32 s76, s33, s8
	s_addc_u32 s77, s44, s9
	s_and_b64 s[8:9], s[4:5], exec
	s_cselect_b32 s57, s77, s35
	s_cselect_b32 s90, s76, s34
	s_ashr_i32 s25, s24, 31
	s_lshl_b64 s[8:9], s[24:25], 21
	s_add_u32 s80, s45, s8
	s_addc_u32 s81, s53, s9
	s_and_b64 s[8:9], s[4:5], exec
	s_cselect_b32 s25, s81, s7
	s_cselect_b32 s91, s80, s6
	s_add_u32 s96, s6, 0x100
	s_addc_u32 vcc_lo, s7, 0
	s_add_u32 s6, s34, 0x100080
	v_mov_b32_e32 v0, 0
	s_addc_u32 s7, s35, 0
	s_mov_b32 vcc_hi, -2
	v_mov_b32_e32 v1, v0
	v_mov_b32_e32 v2, v0
	v_mov_b32_e32 v3, v0
	v_mov_b32_e32 v4, v0
	v_mov_b32_e32 v5, v0
	v_mov_b32_e32 v6, v0
	v_mov_b32_e32 v7, v0
	v_mov_b32_e32 v16, v0
	v_mov_b32_e32 v17, v0
	v_mov_b32_e32 v18, v0
	v_mov_b32_e32 v19, v0
	v_mov_b32_e32 v20, v0
	v_mov_b32_e32 v21, v0
	v_mov_b32_e32 v22, v0
	v_mov_b32_e32 v23, v0
	v_mov_b32_e32 v32, v0
	v_mov_b32_e32 v33, v0
	v_mov_b32_e32 v34, v0
	v_mov_b32_e32 v35, v0
	v_mov_b32_e32 v36, v0
	v_mov_b32_e32 v37, v0
	v_mov_b32_e32 v38, v0
	v_mov_b32_e32 v39, v0
	v_mov_b32_e32 v48, v0
	v_mov_b32_e32 v49, v0
	v_mov_b32_e32 v50, v0
	v_mov_b32_e32 v51, v0
	v_mov_b32_e32 v52, v0
	v_mov_b32_e32 v53, v0
	v_mov_b32_e32 v54, v0
	v_mov_b32_e32 v55, v0
	v_mov_b32_e32 v8, v0
	v_mov_b32_e32 v9, v0
	v_mov_b32_e32 v10, v0
	v_mov_b32_e32 v11, v0
	v_mov_b32_e32 v12, v0
	v_mov_b32_e32 v13, v0
	v_mov_b32_e32 v14, v0
	v_mov_b32_e32 v15, v0
	v_mov_b32_e32 v24, v0
	v_mov_b32_e32 v25, v0
	v_mov_b32_e32 v26, v0
	v_mov_b32_e32 v27, v0
	v_mov_b32_e32 v28, v0
	v_mov_b32_e32 v29, v0
	v_mov_b32_e32 v30, v0
	v_mov_b32_e32 v31, v0
	v_mov_b32_e32 v40, v0
	v_mov_b32_e32 v41, v0
	v_mov_b32_e32 v42, v0
	v_mov_b32_e32 v43, v0
	v_mov_b32_e32 v44, v0
	v_mov_b32_e32 v45, v0
	v_mov_b32_e32 v46, v0
	v_mov_b32_e32 v47, v0
	v_mov_b32_e32 v56, v0
	v_mov_b32_e32 v57, v0
	v_mov_b32_e32 v58, v0
	v_mov_b32_e32 v59, v0
	v_mov_b32_e32 v60, v0
	v_mov_b32_e32 v61, v0
	v_mov_b32_e32 v62, v0
	v_mov_b32_e32 v63, v0
	v_mov_b32_e32 v86, v0
	v_mov_b32_e32 v87, v0
	v_mov_b32_e32 v88, v0
	v_mov_b32_e32 v89, v0
	v_mov_b32_e32 v94, v0
	v_mov_b32_e32 v95, v0
	v_mov_b32_e32 v96, v0
	v_mov_b32_e32 v97, v0
	v_mov_b32_e32 v114, v0
	v_mov_b32_e32 v115, v0
	v_mov_b32_e32 v116, v0
	v_mov_b32_e32 v117, v0
	v_mov_b32_e32 v118, v0
	v_mov_b32_e32 v119, v0
	v_mov_b32_e32 v120, v0
	v_mov_b32_e32 v121, v0
	v_mov_b32_e32 v130, v0
	v_mov_b32_e32 v131, v0
	v_mov_b32_e32 v132, v0
	v_mov_b32_e32 v133, v0
	v_mov_b32_e32 v134, v0
	v_mov_b32_e32 v135, v0
	v_mov_b32_e32 v136, v0
	v_mov_b32_e32 v137, v0
	v_mov_b32_e32 v146, v0
	v_mov_b32_e32 v147, v0
	v_mov_b32_e32 v148, v0
	v_mov_b32_e32 v149, v0
	v_mov_b32_e32 v150, v0
	v_mov_b32_e32 v151, v0
	v_mov_b32_e32 v152, v0
	v_mov_b32_e32 v153, v0
	v_mov_b32_e32 v106, v0
	v_mov_b32_e32 v107, v0
	v_mov_b32_e32 v108, v0
	v_mov_b32_e32 v109, v0
	v_mov_b32_e32 v110, v0
	v_mov_b32_e32 v111, v0
	v_mov_b32_e32 v112, v0
	v_mov_b32_e32 v113, v0
	v_mov_b32_e32 v122, v0
	v_mov_b32_e32 v123, v0
	v_mov_b32_e32 v124, v0
	v_mov_b32_e32 v125, v0
	v_mov_b32_e32 v126, v0
	v_mov_b32_e32 v127, v0
	v_mov_b32_e32 v128, v0
	v_mov_b32_e32 v129, v0
	v_mov_b32_e32 v138, v0
	v_mov_b32_e32 v139, v0
	v_mov_b32_e32 v140, v0
	v_mov_b32_e32 v141, v0
	v_mov_b32_e32 v142, v0
	v_mov_b32_e32 v143, v0
	v_mov_b32_e32 v144, v0
	v_mov_b32_e32 v145, v0
	v_mov_b32_e32 v154, v0
	v_mov_b32_e32 v155, v0
	v_mov_b32_e32 v156, v0
	v_mov_b32_e32 v157, v0
	v_mov_b32_e32 v158, v0
	v_mov_b32_e32 v159, v0
	v_mov_b32_e32 v160, v0
	v_mov_b32_e32 v161, v0
	.p2align 6
